# v62 + hgC dynamic work queue split into 8 queues by blockIdx&7 (each hands out 128 items) to avoid serializing ~1500 returning atomics on one word
# speedup vs baseline: 1.0226x; 1.0226x over previous
; __device__ __forceinline__ void hgC_loop(Frame& F, unsigned* ctr) {
;     ...
;     if (tid == 0) { slot[0] = (int)__hip_atomic_fetch_add(ctr, 1u, __ATOMIC_RELAXED, __HIP_MEMORY_SCOPE_AGENT); slot[1] = (int)__hip_atomic_fetch_add(ctr, 1u, __ATOMIC_RELAXED, __HIP_MEMORY_SCOPE_AGENT); }
;     __syncthreads();
;     int item = slot[0], nxt = slot[1], par = 0;
;     if (item >= 1024) return;
.LBB0_684:
	s_add_u32 s4, s50, 0x8000
	s_addc_u32 s5, s51, 0
	s_and_b32 s3, s2, 7
	s_lshl_b32 s29, s3, 7
	s_lshl_b32 s3, s3, 8
	s_add_u32 s4, s4, s3
	s_addc_u32 s5, s5, 0
	v_mov_b32_e32 v237, 0x400
	s_waitcnt vmcnt(0)
	s_barrier
	s_and_saveexec_b64 s[0:1], s[92:93]
	s_cbranch_execz .LBB0_690
	s_mov_b64 s[12:13], exec
	v_mbcnt_lo_u32_b32 v2, s12, 0
	v_mbcnt_hi_u32_b32 v2, s13, v2
	v_cmp_eq_u32_e32 vcc, 0, v2
	s_and_saveexec_b64 s[10:11], vcc
	s_cbranch_execz .LBB0_687
	s_bcnt1_i32_b64 s3, s[12:13]
	v_mov_b32_e32 v3, 0
	v_mov_b32_e32 v4, s3
	global_atomic_add v3, v3, v4, s[4:5] sc0
.LBB0_687:
	s_or_b64 exec, exec, s[10:11]
	s_waitcnt vmcnt(0)
	v_readfirstlane_b32 s3, v3
	s_mov_b64 s[10:11], exec
	s_nop 0
	v_add_u32_e32 v3, s3, v2
	v_mov_b32_e32 v2, 0
	v_cmp_gt_u32_e32 vcc, 0x80, v3
	v_add_u32_e32 v3, s29, v3
	s_nop 1
	v_cndmask_b32_e32 v3, v237, v3, vcc
	ds_write_b32 v2, v3 offset:53248
	v_mbcnt_lo_u32_b32 v3, s10, 0
	v_mbcnt_hi_u32_b32 v3, s11, v3
	v_cmp_eq_u32_e32 vcc, 0, v3
	s_and_saveexec_b64 s[12:13], vcc
	s_cbranch_execz .LBB0_689
	s_bcnt1_i32_b64 s3, s[10:11]
	v_mov_b32_e32 v4, s3
	global_atomic_add v4, v2, v4, s[4:5] sc0
.LBB0_689:
	s_or_b64 exec, exec, s[12:13]
	s_waitcnt vmcnt(0)
	v_readfirstlane_b32 s3, v4
	s_nop 1
	v_add_u32_e32 v3, s3, v3
	v_cmp_gt_u32_e32 vcc, 0x80, v3
	v_add_u32_e32 v3, s29, v3
	s_nop 1
	v_cndmask_b32_e32 v3, v237, v3, vcc
	ds_write_b32 v2, v3 offset:53252

; __device__ __forceinline__ void hgC_loop(Frame& F, unsigned* ctr) {
;     ...
;         if (tid == 0) slot[par] = (int)__hip_atomic_fetch_add(ctr, 1u, __ATOMIC_RELAXED, __HIP_MEMORY_SCOPE_AGENT);
.LBB0_696:
	s_or_b64 exec, exec, s[22:23]
	v_lshlrev_b32_e32 v4, 2, v99
	s_waitcnt vmcnt(0)
	v_readfirstlane_b32 s10, v3
	v_add_u32_e32 v4, 0, v4
	s_nop 0
	v_add_u32_e32 v2, s10, v2
	v_cmp_gt_u32_e32 vcc, 0x80, v2
	v_add_u32_e32 v2, s29, v2
	s_nop 1
	v_cndmask_b32_e32 v2, v237, v2, vcc
	ds_write_b32 v4, v2 offset:53248
